# all four GEMMs: slack workgroups start late, up-proj additionally staggers start in 4 groups of 0.9 us
# baseline (speedup 1.0000x reference)
; __device__ __forceinline__ int opaque_tid() { int t = threadIdx.x; asm volatile("" : "+v"(t)); return t; }
; #define PG8_STAGE(bufoff, gbase, voff) do { _Pragma("unroll") for (int _i = 0; _i < 2; ++_i) \
;         __builtin_amdgcn_global_load_lds((const unsigned*)((const char*)(gbase) + (voff)[_i]), (LAS unsigned*)(lds + (bufoff) + ldsw + _i * 8192), 16, 0, 0); } while (0)
; template <class Epi, class Sched>
; __device__ __forceinline__ void gemm_phase(LAS unsigned char* lds, const Gemm g, const Sched& S, const Epi& E) {
;     const int tid = opaque_tid(), wid = __builtin_amdgcn_readfirstlane(tid >> 6), lane = tid & 63, wr = wid >> 2, wc = wid & 3, fr = lane & 15, fq = lane >> 4;
;     const int K = g.K, nt = K / BK;
;     unsigned voffA[2], voffB[2];
; #pragma unroll
;     for (int i = 0; i < 2; ++i) { int R, C; stage_rc(tid * 16 + i * 8192, R, C); const int Rb = Epi::PERM ? ((R & ~31) + perm32(R & 31)) : R;
;         voffA[i] = (unsigned)(R * K + C) * 2u; voffB[i] = (unsigned)(Rb * K + C) * 2u; }
;     ...
;     const char* cA = (const char*)g.A + (size_t)cur.pm * tstep; const char* cB = (const char*)g.Bt + (size_t)cur.pn * tstep;
;     S.a_ready(cur);
;     PG8_STAGE(PG8_SB(0, 0), cB, voffB); PG8_STAGE(PG8_SA(0, 0), cA, voffA); PG8_STAGE(PG8_SB(0, 1), cB + hstep, voffB); PG8_STAGE(PG8_SA(0, 1), cA + hstep, voffA);
.LBB0_180:
	s_or_b64 exec, exec, s[0:1]
	v_readlane_b32 s0, v240, 24
	v_readlane_b32 s1, v240, 25
	s_mov_b32 s1, s3
	v_writelane_b32 v240, s0, 24
	s_waitcnt lgkmcnt(0)
	v_mov_b32_e32 v0, v135
	v_writelane_b32 v240, s1, 25
	v_readlane_b32 s0, v243, 39
	v_readlane_b32 s1, v243, 40
	s_barrier
	s_andn2_b64 vcc, exec, s[0:1]
	v_readfirstlane_b32 s5, v0
	s_cbranch_vccnz .LBB0_192
	v_lshlrev_b32_e32 v4, 4, v0
	v_add_u32_e32 v2, 0x2000, v4
	v_ashrrev_i32_e32 v1, 31, v2
	v_lshrrev_b32_e32 v1, 22, v1
	v_add_u32_e32 v1, v2, v1
	v_ashrrev_i32_e32 v1, 10, v1
	v_mul_i32_i24_e32 v3, 0x400, v1
	v_sub_u32_e32 v2, v2, v3
	v_lshrrev_b32_e32 v3, 4, v2
	v_bitop3_b32 v3, v3, v2, 32 bitop3:0x6c
	v_ashrrev_i32_e32 v2, 31, v3
	v_lshrrev_b32_e32 v2, 26, v2
	v_add_u32_e32 v5, v3, v2
	v_lshlrev_b32_e32 v6, 3, v1
	v_ashrrev_i32_e32 v2, 6, v5
	v_and_b32_e32 v6, -16, v6
	v_add_u32_e32 v6, v2, v6
	v_and_b32_e32 v7, 3, v2
	s_mov_b32 s2, 0x1fffe0
	v_lshrrev_b32_e32 v9, 2, v6
	v_lshlrev_b32_e32 v10, 1, v6
	v_and_b32_e32 v5, 0xc0, v5
	v_and_or_b32 v7, v6, s2, v7
	v_and_b32_e32 v9, 4, v9
	v_and_b32_e32 v10, 24, v10
	v_sub_u32_e32 v3, v3, v5
	v_or3_b32 v7, v7, v9, v10
	v_lshlrev_b32_e32 v9, 5, v1
	v_ashrrev_i16_sdwa v3, v176, sext(v3) dst_sel:DWORD dst_unused:UNUSED_PAD src0_sel:DWORD src1_sel:BYTE_0
	v_and_b32_e32 v9, 32, v9
	v_bfe_i32 v3, v3, 0, 16
	v_add_lshl_u32 v5, v9, v3, 1
	v_lshl_add_u32 v140, v7, 11, v5
	v_lshl_add_u32 v142, v6, 11, v5
	v_bfe_i32 v5, v0, 27, 1
	v_lshrrev_b32_e32 v5, 22, v5
	v_add_u32_e32 v5, v4, v5
	v_and_b32_e32 v5, 0xfffffc00, v5
	v_sub_u32_e32 v4, v4, v5
	v_lshrrev_b32_e32 v5, 4, v4
	v_bitop3_b32 v6, v5, v4, 32 bitop3:0x6c
	v_ashrrev_i32_e32 v5, 31, v0
	v_lshrrev_b32_e32 v5, 26, v5
	v_ashrrev_i32_e32 v4, 31, v4
	v_add_u32_e32 v5, v0, v5
	v_lshrrev_b32_e32 v4, 26, v4
	v_ashrrev_i32_e32 v5, 6, v5
	v_add_u32_e32 v4, v6, v4
	v_lshlrev_b32_e32 v7, 3, v5
	v_ashrrev_i32_e32 v4, 6, v4
	v_and_b32_e32 v7, -16, v7
	v_add_u32_e32 v7, v4, v7
	v_readlane_b32 s0, v240, 24
	v_and_b32_e32 v9, 3, v4
	v_lshrrev_b32_e32 v10, 2, v7
	v_lshlrev_b32_e32 v11, 1, v7
	s_mul_i32 s0, s0, 0x700000
	v_and_or_b32 v9, v7, s2, v9
	v_and_b32_e32 v10, 4, v10
	v_and_b32_e32 v11, 24, v11
	v_readlane_b32 s1, v240, 25
	s_add_u32 s6, s62, s0
	v_or3_b32 v9, v9, v10, v11
	v_mul_i32_i24_e32 v11, 64, v4
	s_addc_u32 s7, s63, 0
	s_ashr_i32 s1, s5, 6
	v_sub_u32_e32 v6, v6, v11
	s_ashr_i32 s0, s5, 8
	s_lshl_b32 s8, s1, 10
	v_lshlrev_b32_e32 v10, 5, v5
	v_ashrrev_i16_sdwa v6, v176, sext(v6) dst_sel:DWORD dst_unused:UNUSED_PAD src0_sel:DWORD src1_sel:BYTE_0
	v_readlane_b32 s10, v241, 18
	v_and_b32_e32 v10, 32, v10
	v_bfe_i32 v6, v6, 0, 16
	v_readlane_b32 s11, v241, 19
	s_add_u32 s66, s6, s10
	v_add_lshl_u32 v10, v10, v6, 1
	s_addc_u32 s67, s7, s11
	s_add_i32 s9, s8, 16
	v_lshl_add_u32 v144, v9, 11, v10
	s_cmp_lg_u32 s46, 0x100
	s_cbranch_scc1 .Lds184_x
	s_movk_i32 s99, 0x70
	s_cmp_eq_u32 s99, 0
	s_cbranch_scc1 .Lds184_n
	s_cmp_lt_u32 s92, s99
	s_cbranch_scc1 .Lds184_c
	s_sub_u32 s98, s92, s99
	s_mul_i32 s98, s98, 1024
	s_lshr_b32 s98, s98, 12
	s_add_u32 s98, s98, 36
	s_branch .Lds184_s

; #define PG8_STAGE(bufoff, gbase, voff) do { _Pragma("unroll") for (int _i = 0; _i < 2; ++_i) \
;         __builtin_amdgcn_global_load_lds((const unsigned*)((const char*)(gbase) + (voff)[_i]), (LAS unsigned*)(lds + (bufoff) + ldsw + _i * 8192), 16, 0, 0); } while (0)
; template <class Epi, class Sched>
; __device__ __forceinline__ void gemm_phase(LAS unsigned char* lds, const Gemm g, const Sched& S, const Epi& E) {
;     ...
;     S.a_ready(cur);
;     PG8_STAGE(PG8_SB(0, 0), cB, voffB); PG8_STAGE(PG8_SA(0, 0), cA, voffA); PG8_STAGE(PG8_SB(0, 1), cB + hstep, voffB); PG8_STAGE(PG8_SA(0, 1), cA + hstep, voffA);
.Lds184_z:
	s_cmp_eq_u32 s98, 0
	s_cbranch_scc1 .Lds184_x
.Lds184_s:
	s_min_u32 s98, s98, 100
.Lds184_l:
	s_sleep 8
	s_sub_u32 s98, s98, 1
	s_cmp_gt_i32 s98, 0
	s_cbranch_scc1 .Lds184_l

; #define PG8_STAGE(bufoff, gbase, voff) do { _Pragma("unroll") for (int _i = 0; _i < 2; ++_i) \
;         __builtin_amdgcn_global_load_lds((const unsigned*)((const char*)(gbase) + (voff)[_i]), (LAS unsigned*)(lds + (bufoff) + ldsw + _i * 8192), 16, 0, 0); } while (0)
; #define PG8_WAIT_V(n) asm volatile("s_waitcnt vmcnt(" #n ")" ::: "memory")
; #define PG8_BAR __builtin_amdgcn_s_barrier()
; template <class Epi, class Sched>
; __device__ __forceinline__ void gemm_phase(LAS unsigned char* lds, const Gemm g, const Sched& S, const Epi& E) {
;     ...
;     const unsigned ldsw = (unsigned)wid * 1024u;
;     const int aoff = lds_byte(wr * 64 + fr, fq * 8), boff = lds_byte(wc * 32 + fr, fq * 8);
;     ...
;     PG8_STAGE(PG8_SB(0, 0), cB, voffB); PG8_STAGE(PG8_SA(0, 0), cA, voffA); PG8_STAGE(PG8_SB(0, 1), cB + hstep, voffB); PG8_STAGE(PG8_SA(0, 1), cA + hstep, voffA);
;     if (wr == 1) PG8_BAR;
;     PG8_WAIT_V(4); PG8_BAR;
;     PG8_STAGE(PG8_SB(1, 0), cB + kstep, voffB); PG8_STAGE(PG8_SA(1, 0), cA + kstep, voffA); PG8_STAGE(PG8_SB(1, 1), cB + hstep + kstep, voffB);
;     PG8_WAIT_V(6); PG8_BAR;
.LBB0_511:
	v_lshrrev_b32_e32 v18, 1, v6
	v_and_b32_e32 v18, 24, v18
	s_lshl_b32 s13, s13, 5
	v_mov_b32_e32 v145, v8
	v_and_b32_e32 v7, 15, v6
	v_lshlrev_b32_e32 v19, 1, v18
	v_lshlrev_b32_e32 v6, 2, v6
	s_and_b32 s15, s13, 0x60
	v_lshl_add_u64 v[10:11], s[74:75], 0, v[144:145]
	v_mov_b32_e32 v141, v8
	v_lshl_or_b32 v9, s14, 6, v7
	v_lshl_or_b32 v7, v7, 6, v19
	s_lshl_b32 s14, s14, 13
	v_and_b32_e32 v6, 32, v6
	s_lshl_b32 s13, s15, 7
	v_lshl_add_u64 v[12:13], s[74:75], 0, v[140:141]
	v_mov_b32_e32 v147, v8
	v_bitop3_b32 v19, v7, s14, v6 bitop3:0xde
	v_bitop3_b32 v152, v7, s13, v6 bitop3:0xde
	s_add_i32 m0, s1, 0x18000
	v_lshl_add_u64 v[6:7], v[10:11], 0, s[94:95]
	v_lshl_add_u64 v[14:15], s[72:73], 0, v[146:147]
	v_mov_b32_e32 v143, v8
	s_waitcnt vmcnt(4)
	s_barrier
	global_load_lds_dwordx4 v[6:7], off
	v_lshl_add_u64 v[6:7], v[12:13], 0, s[94:95]
	s_add_i32 m0, s1, 0x1a000
	s_add_i32 s13, s1, 0x8000
	s_add_i32 s14, s1, 0xa000
	v_lshl_add_u64 v[16:17], s[72:73], 0, v[142:143]
	global_load_lds_dwordx4 v[6:7], off
	v_lshl_add_u64 v[6:7], v[14:15], 0, s[94:95]
	s_mov_b32 m0, s13
	s_add_u32 s16, s74, 0x40080
	global_load_lds_dwordx4 v[6:7], off
	v_lshl_add_u64 v[6:7], v[16:17], 0, s[94:95]
	s_mov_b32 m0, s14
	s_addc_u32 s17, s75, 0
	global_load_lds_dwordx4 v[6:7], off
	s_add_i32 m0, s1, 0x1c000
	v_lshl_add_u64 v[6:7], s[16:17], 0, v[144:145]
	global_load_lds_dwordx4 v[6:7], off
	v_lshl_add_u64 v[6:7], s[16:17], 0, v[140:141]
	s_add_i32 m0, s1, 0x1e000
	v_or_b32_e32 v153, s15, v18
	global_load_lds_dwordx4 v[6:7], off
	v_lshlrev_b32_e32 v6, 14, v4
	v_and_b32_e32 v6, 0xffff8000, v6
	v_lshl_add_u32 v3, v3, 11, v6
	v_and_b32_e32 v4, 1, v4
	v_lshl_or_b32 v3, v4, 6, v3
	v_lshl_add_u32 v148, v5, 1, v3
	v_lshlrev_b32_e32 v3, 14, v0
	v_and_b32_e32 v3, 0xffff8000, v3
	s_waitcnt vmcnt(6)
	v_lshl_add_u32 v1, v1, 11, v3
	v_and_b32_e32 v0, 1, v0
	v_lshl_or_b32 v0, v0, 6, v1
	v_mov_b32_e32 v149, v8
	v_lshl_add_u32 v150, v2, 1, v0
	v_mov_b32_e32 v151, v8
	s_mov_b32 s15, 0
	v_add_u32_e32 v154, 16, v19
	s_barrier
	s_cmp_lg_u32 s46, 0x100
	s_cbranch_scc1 .Lds512_x
	s_and_b32 s99, s2, 0xff
	s_cmp_eq_u32 s99, 0
	s_cbranch_scc1 .Lds512_n
	s_cmp_lt_u32 s92, s99
	s_cbranch_scc1 .Lds512_c
	s_mov_b32 s98, 35
	s_branch .Lds512_s

;     __device__ bool next(int i, Unit& u) const {
;         const long L = (long)i * G + c; if (L >= nwg) return false;
;         int wgid = (int)L; { const int q = nwg / NXCD, r = nwg % NXCD, xcd = wgid % NXCD, off = wgid / NXCD; wgid = (xcd < r ? xcd * (q + 1) : r * (q + 1) + (xcd - r) * q) + off; }
;         const int nig = WGM * nN, gid = wgid / nig, fm = gid * WGM, gsz = (nM - fm) < WGM ? (nM - fm) : WGM;
;         u.pm = fm + ((wgid % nig) % gsz); u.pn = (wgid % nig) / gsz; return true;
;     }
.Lds512_x:
.LBB0_512:
	s_add_i32 s15, s15, 1
	s_mul_i32 s16, s15, s93
	s_mul_hi_u32 s17, s15, s46
	s_add_i32 s17, s17, s16
	s_mul_i32 s16, s15, s46
	s_add_u32 s66, s16, s92
	s_addc_u32 s67, s17, s45
	v_mov_b64_e32 v[0:1], s[2:3]
	v_cmp_ge_i64_e64 s[38:39], s[66:67], v[0:1]
	s_and_b64 vcc, exec, s[38:39]
	s_cbranch_vccnz .LBB0_514
	s_ashr_i32 s16, s66, 31
	s_lshr_b32 s16, s16, 29
	s_add_i32 s16, s66, s16
	s_ashr_i32 s17, s16, 3
	s_and_b32 s16, s16, -8
	s_sub_i32 s16, s66, s16
	s_lshr_b32 s18, s16, 31
	s_or_b32 s18, s10, s18
	s_mul_i32 s16, s18, s16
	s_add_i32 s16, s16, s17
	s_ashr_i32 s17, s16, 31
	s_lshr_b32 s17, s17, 27
	s_add_i32 s17, s16, s17
	s_ashr_i32 s18, s17, 5
	s_lshl_b32 s18, s18, 3
	s_sub_i32 s19, s5, s18
	s_min_i32 s19, s19, 8
	s_abs_i32 s20, s19
	v_cvt_f32_u32_e32 v0, s20
	s_sub_i32 s22, 0, s20
	s_andn2_b32 s17, s17, 31
	s_sub_i32 s16, s16, s17
	v_rcp_iflag_f32_e32 v0, v0
	s_abs_i32 s17, s16
	s_xor_b32 s21, s16, s19
	s_ashr_i32 s21, s21, 31
	v_mul_f32_e32 v0, 0x4f7ffffe, v0
	v_cvt_u32_f32_e32 v0, v0
	s_nop 0
	v_readfirstlane_b32 s23, v0
	s_mul_i32 s22, s22, s23
	s_mul_hi_u32 s22, s23, s22
	s_add_i32 s23, s23, s22
	s_mul_hi_u32 s22, s17, s23
	s_mul_i32 s23, s22, s20
	s_sub_i32 s17, s17, s23
	s_add_i32 s42, s22, 1
	s_sub_i32 s23, s17, s20
	s_cmp_ge_u32 s17, s20
	s_cselect_b32 s22, s42, s22
	s_cselect_b32 s17, s23, s17
	s_add_i32 s23, s22, 1
	s_cmp_ge_u32 s17, s20
	s_cselect_b32 s17, s23, s22
	s_xor_b32 s17, s17, s21
	s_sub_i32 s42, s17, s21
	s_mul_i32 s17, s42, s19
	s_sub_i32 s16, s16, s17
	s_add_i32 s88, s16, s18

; #define PG8_STAGE(bufoff, gbase, voff) do { _Pragma("unroll") for (int _i = 0; _i < 2; ++_i) \
;         __builtin_amdgcn_global_load_lds((const unsigned*)((const char*)(gbase) + (voff)[_i]), (LAS unsigned*)(lds + (bufoff) + ldsw + _i * 8192), 16, 0, 0); } while (0)
; #define PG8_WAIT_V(n) asm volatile("s_waitcnt vmcnt(" #n ")" ::: "memory")
; #define PG8_BAR __builtin_amdgcn_s_barrier()
; template <class Epi, class Sched>
; __device__ __forceinline__ void gemm_phase(LAS unsigned char* lds, const Gemm g, const Sched& S, const Epi& E) {
;     ...
;     const unsigned ldsw = (unsigned)wid * 1024u;
;     const int aoff = lds_byte(wr * 64 + fr, fq * 8), boff = lds_byte(wc * 32 + fr, fq * 8);
;     ...
;     PG8_STAGE(PG8_SB(0, 0), cB, voffB); PG8_STAGE(PG8_SA(0, 0), cA, voffA); PG8_STAGE(PG8_SB(0, 1), cB + hstep, voffB); PG8_STAGE(PG8_SA(0, 1), cA + hstep, voffA);
;     if (wr == 1) PG8_BAR;
;     PG8_WAIT_V(4); PG8_BAR;
;     PG8_STAGE(PG8_SB(1, 0), cB + kstep, voffB); PG8_STAGE(PG8_SA(1, 0), cA + kstep, voffA); PG8_STAGE(PG8_SB(1, 1), cB + hstep + kstep, voffB);
;     PG8_WAIT_V(6); PG8_BAR;
.LBB0_642:
	v_lshrrev_b32_e32 v18, 1, v6
	v_and_b32_e32 v18, 24, v18
	s_lshl_b32 s1, s1, 5
	v_mov_b32_e32 v145, v8
	v_and_b32_e32 v7, 15, v6
	v_lshlrev_b32_e32 v19, 1, v18
	v_lshlrev_b32_e32 v6, 2, v6
	s_and_b32 s18, s1, 0x60
	v_lshl_add_u64 v[10:11], s[70:71], 0, v[144:145]
	v_mov_b32_e32 v141, v8
	v_lshl_or_b32 v9, s14, 6, v7
	v_lshl_or_b32 v7, v7, 6, v19
	s_lshl_b32 s14, s14, 13
	v_and_b32_e32 v6, 32, v6
	s_lshl_b32 s1, s18, 7
	v_lshl_add_u64 v[12:13], s[70:71], 0, v[140:141]
	v_mov_b32_e32 v147, v8
	v_bitop3_b32 v19, v7, s14, v6 bitop3:0xde
	v_bitop3_b32 v152, v7, s1, v6 bitop3:0xde
	s_add_i32 m0, s11, 0x18000
	v_lshl_add_u64 v[6:7], v[10:11], 0, s[94:95]
	v_lshl_add_u64 v[14:15], s[78:79], 0, v[146:147]
	v_mov_b32_e32 v143, v8
	s_waitcnt vmcnt(4)
	s_barrier
	global_load_lds_dwordx4 v[6:7], off
	v_lshl_add_u64 v[6:7], v[12:13], 0, s[94:95]
	s_add_i32 m0, s11, 0x1a000
	s_add_i32 s14, s11, 0x8000
	s_add_i32 s15, s11, 0xa000
	v_lshl_add_u64 v[16:17], s[78:79], 0, v[142:143]
	global_load_lds_dwordx4 v[6:7], off
	v_lshl_add_u64 v[6:7], v[14:15], 0, s[94:95]
	s_mov_b32 m0, s14
	s_add_u32 s16, s70, 0x40080
	global_load_lds_dwordx4 v[6:7], off
	v_lshl_add_u64 v[6:7], v[16:17], 0, s[94:95]
	s_mov_b32 m0, s15
	s_addc_u32 s17, s71, 0
	global_load_lds_dwordx4 v[6:7], off
	s_add_i32 m0, s11, 0x1c000
	v_lshl_add_u64 v[6:7], s[16:17], 0, v[144:145]
	global_load_lds_dwordx4 v[6:7], off
	v_lshl_add_u64 v[6:7], s[16:17], 0, v[140:141]
	s_add_i32 m0, s11, 0x1e000
	s_mov_b32 s1, s3
	global_load_lds_dwordx4 v[6:7], off
	v_lshlrev_b32_e32 v6, 14, v4
	v_and_b32_e32 v6, 0xffff8000, v6
	v_lshl_add_u32 v3, v3, 11, v6
	v_and_b32_e32 v4, 1, v4
	v_lshl_or_b32 v3, v4, 6, v3
	v_lshl_add_u32 v148, v5, 1, v3
	v_lshlrev_b32_e32 v3, 14, v0
	v_and_b32_e32 v3, 0xffff8000, v3
	s_waitcnt vmcnt(6)
	v_lshl_add_u32 v1, v1, 11, v3
	v_and_b32_e32 v0, 1, v0
	v_lshl_or_b32 v0, v0, 6, v1
	v_or_b32_e32 v153, s18, v18
	v_mov_b32_e32 v149, v8
	v_lshl_add_u32 v150, v2, 1, v0
	v_mov_b32_e32 v151, v8
	s_mov_b32 s43, 0
	v_add_u32_e32 v154, 16, v19
	s_barrier
	s_cmp_lg_u32 s46, 0x100
	s_cbranch_scc1 .Lds643_x
	s_and_b32 s99, s0, 0xff
	s_cmp_eq_u32 s99, 0
	s_cbranch_scc1 .Lds643_n
	s_cmp_lt_u32 s92, s99
	s_cbranch_scc1 .Lds643_c
	s_sub_u32 s98, s92, s99
	s_mul_i32 s98, s98, 1792
	s_lshr_b32 s98, s98, 12
	s_add_u32 s98, s98, 35
	s_branch .Lds643_s
.Lds643_n:
	s_bfe_u32 s98, s92, 0x20003
	s_mul_i32 s98, s98, 4
	s_branch .Lds643_z
.Lds643_c:
	s_bfe_u32 s98, s92, 0x20003
	s_mul_i32 s98, s98, 4

;     __device__ bool next(int i, Unit& u) const {
;         const long L = (long)i * G + c; if (L >= nwg) return false;
;         int wgid = (int)L; { const int q = nwg / NXCD, r = nwg % NXCD, xcd = wgid % NXCD, off = wgid / NXCD; wgid = (xcd < r ? xcd * (q + 1) : r * (q + 1) + (xcd - r) * q) + off; }
;         const int nig = WGM * nN, gid = wgid / nig, fm = gid * WGM, gsz = (nM - fm) < WGM ? (nM - fm) : WGM;
;         u.pm = fm + ((wgid % nig) % gsz); u.pn = (wgid % nig) / gsz; return true;
;     }
.Lds643_x:
.LBB0_643:
	s_add_i32 s43, s43, 1
	s_mul_i32 s16, s43, s93
	s_mul_hi_u32 s17, s43, s46
	s_add_i32 s17, s17, s16
	s_mul_i32 s16, s43, s46
	s_add_u32 s66, s16, s92
	s_addc_u32 s67, s17, s45
	v_mov_b64_e32 v[0:1], s[0:1]
	v_cmp_ge_i64_e64 s[38:39], s[66:67], v[0:1]
	s_and_b64 vcc, exec, s[38:39]
	s_cbranch_vccnz .LBB0_645
	s_ashr_i32 s16, s66, 31
	s_lshr_b32 s16, s16, 29
	s_add_i32 s16, s66, s16
	s_ashr_i32 s17, s16, 3
	s_and_b32 s16, s16, -8
	s_sub_i32 s16, s66, s16
	s_lshr_b32 s18, s16, 31
	s_or_b32 s18, s10, s18
	s_mul_i32 s16, s18, s16
	s_add_i32 s16, s16, s17
	s_mul_hi_i32 s17, s16, 0x2e8ba2e9
	s_lshr_b32 s18, s17, 31
	s_ashr_i32 s17, s17, 5
	s_add_i32 s17, s17, s18
	s_lshl_b32 s18, s17, 3
	s_sub_i32 s19, s5, s18
	s_min_i32 s19, s19, 8
	s_abs_i32 s20, s19
	v_cvt_f32_u32_e32 v0, s20
	s_sub_i32 s22, 0, s20
	s_mulk_i32 s17, 0xb0
	s_sub_i32 s16, s16, s17
	v_rcp_iflag_f32_e32 v0, v0
	s_abs_i32 s17, s16
	s_xor_b32 s21, s16, s19
	s_ashr_i32 s21, s21, 31
	v_mul_f32_e32 v0, 0x4f7ffffe, v0
	v_cvt_u32_f32_e32 v0, v0
	s_nop 0
	v_readfirstlane_b32 s23, v0
	s_mul_i32 s22, s22, s23
	s_mul_hi_u32 s22, s23, s22
	s_add_i32 s23, s23, s22
	s_mul_hi_u32 s22, s17, s23
	s_mul_i32 s23, s22, s20
	s_sub_i32 s17, s17, s23
	s_add_i32 s72, s22, 1
	s_sub_i32 s23, s17, s20
	s_cmp_ge_u32 s17, s20
	s_cselect_b32 s22, s72, s22
	s_cselect_b32 s17, s23, s17
	s_add_i32 s23, s22, 1
	s_cmp_ge_u32 s17, s20
	s_cselect_b32 s17, s23, s22
	s_xor_b32 s17, s17, s21
	s_sub_i32 s72, s17, s21
	s_mul_i32 s17, s72, s19
	s_sub_i32 s16, s16, s17
	s_add_i32 s74, s16, s18

; #define PG8_STAGE(bufoff, gbase, voff) do { _Pragma("unroll") for (int _i = 0; _i < 2; ++_i) \
;         __builtin_amdgcn_global_load_lds((const unsigned*)((const char*)(gbase) + (voff)[_i]), (LAS unsigned*)(lds + (bufoff) + ldsw + _i * 8192), 16, 0, 0); } while (0)
; #define PG8_WAIT_V(n) asm volatile("s_waitcnt vmcnt(" #n ")" ::: "memory")
; #define PG8_BAR __builtin_amdgcn_s_barrier()
; template <class Epi, class Sched>
; __device__ __forceinline__ void gemm_phase(LAS unsigned char* lds, const Gemm g, const Sched& S, const Epi& E) {
;     ...
;     const unsigned ldsw = (unsigned)wid * 1024u;
;     const int aoff = lds_byte(wr * 64 + fr, fq * 8), boff = lds_byte(wc * 32 + fr, fq * 8);
;     ...
;     PG8_STAGE(PG8_SB(0, 0), cB, voffB); PG8_STAGE(PG8_SA(0, 0), cA, voffA); PG8_STAGE(PG8_SB(0, 1), cB + hstep, voffB); PG8_STAGE(PG8_SA(0, 1), cA + hstep, voffA);
;     if (wr == 1) PG8_BAR;
;     PG8_WAIT_V(4); PG8_BAR;
;     PG8_STAGE(PG8_SB(1, 0), cB + kstep, voffB); PG8_STAGE(PG8_SA(1, 0), cA + kstep, voffA); PG8_STAGE(PG8_SB(1, 1), cB + hstep + kstep, voffB);
;     PG8_WAIT_V(6); PG8_BAR;
.LBB0_817:
	v_lshrrev_b32_e32 v20, 1, v18
	v_and_b32_e32 v20, 24, v20
	s_lshl_b32 s0, s0, 5
	v_and_b32_e32 v19, 15, v18
	v_lshlrev_b32_e32 v21, 1, v20
	v_lshlrev_b32_e32 v18, 2, v18
	s_and_b32 s16, s0, 0x60
	s_add_i32 m0, s11, 0x18000
	v_lshl_add_u64 v[6:7], v[6:7], 0, s[94:95]
	v_lshl_or_b32 v9, s1, 6, v19
	v_lshl_or_b32 v19, v19, 6, v21
	s_lshl_b32 s1, s1, 13
	v_and_b32_e32 v18, 32, v18
	s_lshl_b32 s0, s16, 7
	s_waitcnt vmcnt(4)
	s_barrier
	global_load_lds_dwordx4 v[6:7], off
	v_lshl_add_u64 v[4:5], v[4:5], 0, s[94:95]
	s_add_i32 m0, s11, 0x1a000
	s_add_i32 s14, s11, 0x8000
	s_add_i32 s15, s11, 0xa000
	v_bitop3_b32 v152, v19, s0, v18 bitop3:0xde
	global_load_lds_dwordx4 v[4:5], off
	v_lshl_add_u64 v[2:3], v[2:3], 0, s[94:95]
	s_mov_b32 m0, s14
	s_add_u32 s0, s72, 0xb0080
	v_bitop3_b32 v21, v19, s1, v18 bitop3:0xde
	global_load_lds_dwordx4 v[2:3], off
	v_lshl_add_u64 v[0:1], v[0:1], 0, s[94:95]
	s_mov_b32 m0, s15
	s_addc_u32 s1, s73, 0
	global_load_lds_dwordx4 v[0:1], off
	s_add_i32 m0, s11, 0x1c000
	v_lshl_add_u64 v[0:1], s[0:1], 0, v[144:145]
	global_load_lds_dwordx4 v[0:1], off
	v_lshl_add_u64 v[0:1], s[0:1], 0, v[140:141]
	s_add_i32 m0, s11, 0x1e000
	v_or_b32_e32 v153, s16, v20
	global_load_lds_dwordx4 v[0:1], off
	v_lshrrev_b32_e32 v1, 1, v15
	v_mul_lo_u32 v0, v14, s20
	s_mov_b32 s16, 0xb000
	v_mad_u64_u32 v[0:1], s[0:1], v1, s16, v[0:1]
	v_or_b32_e32 v0, v0, v16
	v_add_lshl_u32 v0, v0, v17, 1
	v_mov_b32_e32 v1, v8
	s_mov_b64 s[18:19], 0xb0080
	v_lshl_add_u64 v[148:149], v[0:1], 0, s[18:19]
	v_lshrrev_b32_e32 v1, 1, v10
	v_mul_lo_u32 v0, v11, s20
	v_mad_u64_u32 v[0:1], s[0:1], v1, s16, v[0:1]
	s_waitcnt vmcnt(6)
	v_or_b32_e32 v0, v0, v12
	v_add_lshl_u32 v0, v0, v13, 1
	v_mov_b32_e32 v1, v8
	v_lshl_add_u64 v[150:151], v[0:1], 0, s[18:19]
	s_mov_b32 s79, 0
	v_add_u32_e32 v154, 16, v21
	s_barrier
	s_cmp_lg_u32 s46, 0x100
	s_cbranch_scc1 .Lds818_x
	s_and_b32 s99, s2, 0xff
	s_cmp_eq_u32 s99, 0
	s_cbranch_scc1 .Lds818_n
	s_cmp_lt_u32 s92, s99
	s_cbranch_scc1 .Lds818_c
	s_mov_b32 s98, 44
	s_branch .Lds818_s

;     __device__ bool next(int i, Unit& u) const {
;         const long L = (long)i * G + c; if (L >= nwg) return false;
;         int wgid = (int)L; { const int q = nwg / NXCD, r = nwg % NXCD, xcd = wgid % NXCD, off = wgid / NXCD; wgid = (xcd < r ? xcd * (q + 1) : r * (q + 1) + (xcd - r) * q) + off; }
;         const int nig = WGM * nN, gid = wgid / nig, fm = gid * WGM, gsz = (nM - fm) < WGM ? (nM - fm) : WGM;
;         u.pm = fm + ((wgid % nig) % gsz); u.pn = (wgid % nig) / gsz; return true;
;     }
.Lds818_x:
.LBB0_818:
	s_add_i32 s79, s79, 1
	s_mul_i32 s0, s79, s93
	s_mul_hi_u32 s1, s79, s46
	s_add_i32 s1, s1, s0
	s_mul_i32 s0, s79, s46
	s_add_u32 s0, s0, s92
	s_addc_u32 s1, s1, s45
	v_mov_b64_e32 v[0:1], s[2:3]
	v_cmp_ge_i64_e64 s[38:39], s[0:1], v[0:1]
	v_cmp_lt_i64_e64 s[40:41], s[0:1], v[0:1]
	s_and_b64 vcc, exec, s[38:39]
	s_cbranch_vccnz .LBB0_820
	s_ashr_i32 s1, s0, 31
	s_lshr_b32 s1, s1, 29
	s_add_i32 s1, s0, s1
	s_ashr_i32 s16, s1, 3
	s_and_b32 s1, s1, -8
	s_sub_i32 s0, s0, s1
	s_lshr_b32 s1, s0, 31
	s_or_b32 s1, s10, s1
	s_mul_i32 s0, s1, s0
	s_add_i32 s0, s0, s16
	s_ashr_i32 s1, s0, 31
	s_lshr_b32 s1, s1, 27
	s_add_i32 s1, s0, s1
	s_ashr_i32 s16, s1, 5
	s_lshl_b32 s16, s16, 3
	s_sub_i32 s17, s5, s16
	s_min_i32 s17, s17, 8
	s_abs_i32 s18, s17
	v_cvt_f32_u32_e32 v0, s18
	s_sub_i32 s20, 0, s18
	s_andn2_b32 s1, s1, 31
	s_sub_i32 s0, s0, s1
	v_rcp_iflag_f32_e32 v0, v0
	s_abs_i32 s1, s0
	s_xor_b32 s19, s0, s17
	s_ashr_i32 s19, s19, 31
	v_mul_f32_e32 v0, 0x4f7ffffe, v0
	v_cvt_u32_f32_e32 v0, v0
	s_nop 0
	v_readfirstlane_b32 s21, v0
	s_mul_i32 s20, s20, s21
	s_mul_hi_u32 s20, s21, s20
	s_add_i32 s21, s21, s20
	s_mul_hi_u32 s20, s1, s21
	s_mul_i32 s21, s20, s18
	s_sub_i32 s1, s1, s21
	s_add_i32 s22, s20, 1
	s_sub_i32 s21, s1, s18
	s_cmp_ge_u32 s1, s18
	s_cselect_b32 s20, s22, s20
	s_cselect_b32 s1, s21, s1
	s_add_i32 s21, s20, 1
	s_cmp_ge_u32 s1, s18
	s_cselect_b32 s1, s21, s20
	s_xor_b32 s1, s1, s19
	s_sub_i32 s85, s1, s19
	s_mul_i32 s1, s85, s17
	s_sub_i32 s0, s0, s1
	s_add_i32 s88, s0, s16
